# work queues: first item of each queue/layer assigned statically (item = blockIdx) instead of 512 blocks contending on one atomic at phase start; later fetches add the grid size
# speedup vs baseline: 1.0176x; 1.0109x over previous
_Z14fwd_megakernel6Params:
	v_mov_b32_e32 v253, 0
	v_mov_b32_e32 v254, s2
	v_and_b32_e32 v172, 0x3ff, v0
	v_mov_b32_e32 v1, v172
	s_load_dwordx4 s[80:83], s[0:1], 0x180
	s_load_dwordx2 s[14:15], s[0:1], 0x190
	s_add_u32 s8, s0, 0x190
	v_mov_b32_e32 v1, v172
	s_addc_u32 s9, s1, 0
	v_mov_b32_e32 v1, v172
	s_nop 0
	v_cmp_eq_u32_e32 vcc, 0, v1
	s_and_saveexec_b64 s[4:5], vcc
	s_cbranch_execz .LBB0_2
	v_mov_b32_e32 v2, 0
	v_mov_b32_e32 v3, v2
	v_mov_b32_e32 v4, v2
	v_mov_b32_e32 v5, v2
	v_mov_b32_e32 v1, 0x12000
	ds_write_b128 v1, v[2:5]
.LBB0_2:
	s_or_b64 exec, exec, s[4:5]
	s_load_dword s33, s[0:1], 0x198
	s_waitcnt lgkmcnt(0)
	v_mov_b32_e32 v255, s14
	s_barrier
	s_add_u32 s72, s82, 0x1fc7a100
	s_getreg_b32 s3, hwreg(HW_REG_XCC_ID, 0, 4)
	s_addc_u32 s73, s83, 0
	s_and_b32 s3, s3, 15
	v_cmp_ne_u32_e64 s[12:13], 0, v172
	v_cmp_eq_u32_e64 s[74:75], 0, v172
	s_and_saveexec_b64 s[4:5], s[74:75]
	s_cbranch_execz .LBB0_5
	s_mov_b64 s[6:7], exec
	v_mbcnt_lo_u32_b32 v1, s6, 0
	v_mbcnt_hi_u32_b32 v1, s7, v1
	v_cmp_eq_u32_e32 vcc, 0, v1
	s_and_b64 s[10:11], exec, vcc
	s_mov_b64 exec, s[10:11]
	s_cbranch_execz .LBB0_5
	s_lshl_b32 s10, s3, 8
	s_bcnt1_i32_b64 s6, s[6:7]
	v_mov_b32_e32 v1, s10
	v_mov_b32_e32 v2, s6
	global_atomic_add v1, v2, s[72:73] offset:1024

.LBB0_315:
	v_mov_b32_e32 v0, v172
	s_barrier
	s_nop 0
	v_cmp_eq_u32_e32 vcc, 0, v0
	s_and_saveexec_b64 s[0:1], vcc
	s_cbranch_execz .LBB0_319
	s_add_u32 s98, s8, 4
	v_cmp_eq_u32_e32 vcc, s98, v253
	s_nop 4
	s_cbranch_vccnz .Lqf_dyn_1
	v_mov_b32_e32 v253, s98
	v_mov_b32_e32 v0, v254
	s_branch .Lqf_wr_1
.Lqf_dyn_1:
	v_mov_b32_e32 v252, 1
	global_atomic_add v252, v149, v252, s[8:9] offset:4 sc0
	s_waitcnt vmcnt(0)
	v_add_u32_e32 v0, v252, v255
.Lqf_wr_1:
	ds_write_b32 v176, v0

.LBB0_462:
	v_mov_b32_e32 v0, v172
	s_barrier
	s_nop 0
	v_cmp_eq_u32_e32 vcc, 0, v0
	s_and_saveexec_b64 s[0:1], vcc
	s_cbranch_execz .LBB0_466
	s_add_u32 s98, s6, 8
	v_cmp_eq_u32_e32 vcc, s98, v253
	s_nop 4
	s_cbranch_vccnz .Lqf_dyn_2
	v_mov_b32_e32 v253, s98
	v_mov_b32_e32 v0, v254
	s_branch .Lqf_wr_2
.Lqf_dyn_2:
	v_mov_b32_e32 v252, 1
	global_atomic_add v252, v149, v252, s[6:7] offset:8 sc0
	s_waitcnt vmcnt(0)
	v_add_u32_e32 v0, v252, v255

.LBB0_578:
	s_barrier
	s_and_saveexec_b64 s[0:1], s[36:37]
	s_cbranch_execz .LBB0_582
	s_add_u32 s98, s20, 0
	v_cmp_eq_u32_e32 vcc, s98, v253
	s_nop 4
	s_cbranch_vccnz .Lqf_dyn_3
	v_mov_b32_e32 v253, s98
	v_mov_b32_e32 v0, v254
	s_branch .Lqf_wr_3
.Lqf_dyn_3:
	v_mov_b32_e32 v252, 1
	global_atomic_add v252, v149, v252, s[20:21] sc0
	s_waitcnt vmcnt(0)
	v_add_u32_e32 v0, v252, v255

.LBB0_805:
	v_mov_b32_e32 v0, v172
	s_waitcnt lgkmcnt(0)
	s_barrier
	s_nop 0
	v_cmp_eq_u32_e32 vcc, 0, v0
	s_and_saveexec_b64 s[0:1], vcc
	s_cbranch_execz .LBB0_809
	s_add_u32 s98, s26, 12
	v_cmp_eq_u32_e32 vcc, s98, v253
	s_nop 4
	s_cbranch_vccnz .Lqf_dyn_4
	v_mov_b32_e32 v253, s98
	v_add_u32_e32 v0, -16, v254
	s_branch .Lqf_wr_4
.Lqf_dyn_4:
	v_mov_b32_e32 v252, 1
	global_atomic_add v252, v149, v252, s[26:27] offset:12 sc0
	s_waitcnt vmcnt(0)
	v_add_u32_e32 v0, v252, v255
	v_add_u32_e32 v0, -16, v0

	.amdhsa_kernel _Z14fwd_megakernel6Params
		.amdhsa_group_segment_fixed_size 73744
		.amdhsa_private_segment_fixed_size 0
		.amdhsa_kernarg_size 656
		.amdhsa_user_sgpr_count 2
		.amdhsa_user_sgpr_dispatch_ptr 0
		.amdhsa_user_sgpr_queue_ptr 0
		.amdhsa_user_sgpr_kernarg_segment_ptr 1
		.amdhsa_user_sgpr_dispatch_id 0
		.amdhsa_user_sgpr_kernarg_preload_length 0
		.amdhsa_user_sgpr_kernarg_preload_offset 0
		.amdhsa_user_sgpr_private_segment_size 0
		.amdhsa_uses_dynamic_stack 0
		.amdhsa_enable_private_segment 0
		.amdhsa_system_sgpr_workgroup_id_x 1
		.amdhsa_system_sgpr_workgroup_id_y 0
		.amdhsa_system_sgpr_workgroup_id_z 0
		.amdhsa_system_sgpr_workgroup_info 0
		.amdhsa_system_vgpr_workitem_id 2
		.amdhsa_next_free_vgpr 256
		.amdhsa_next_free_sgpr 100
		.amdhsa_accum_offset 256
		.amdhsa_reserve_vcc 1
		.amdhsa_float_round_mode_32 0
		.amdhsa_float_round_mode_16_64 0
		.amdhsa_float_denorm_mode_32 3
		.amdhsa_float_denorm_mode_16_64 3
		.amdhsa_dx10_clamp 1
		.amdhsa_ieee_mode 1
		.amdhsa_fp16_overflow 0
		.amdhsa_tg_split 0
		.amdhsa_exception_fp_ieee_invalid_op 0
		.amdhsa_exception_fp_denorm_src 0
		.amdhsa_exception_fp_ieee_div_zero 0
		.amdhsa_exception_fp_ieee_overflow 0
		.amdhsa_exception_fp_ieee_underflow 0
		.amdhsa_exception_fp_ieee_inexact 0
		.amdhsa_exception_int_div_zero 0
	.end_amdhsa_kernel

amdhsa.kernels:
  - .agpr_count:     0
    .args:
      - .offset:         0
        .size:           400
        .value_kind:     by_value
      - .offset:         400
        .size:           4
        .value_kind:     hidden_block_count_x
      - .offset:         404
        .size:           4
        .value_kind:     hidden_block_count_y
      - .offset:         408
        .size:           4
        .value_kind:     hidden_block_count_z
      - .offset:         412
        .size:           2
        .value_kind:     hidden_group_size_x
      - .offset:         414
        .size:           2
        .value_kind:     hidden_group_size_y
      - .offset:         416
        .size:           2
        .value_kind:     hidden_group_size_z
      - .offset:         418
        .size:           2
        .value_kind:     hidden_remainder_x
      - .offset:         420
        .size:           2
        .value_kind:     hidden_remainder_y
      - .offset:         422
        .size:           2
        .value_kind:     hidden_remainder_z
      - .offset:         440
        .size:           8
        .value_kind:     hidden_global_offset_x
      - .offset:         448
        .size:           8
        .value_kind:     hidden_global_offset_y
      - .offset:         456
        .size:           8
        .value_kind:     hidden_global_offset_z
      - .offset:         464
        .size:           2
        .value_kind:     hidden_grid_dims
      - .offset:         488
        .size:           8
        .value_kind:     hidden_multigrid_sync_arg
    .group_segment_fixed_size: 73744
    .kernarg_segment_align: 8
    .kernarg_segment_size: 656
    .language:       OpenCL C
    .language_version:
      - 2
      - 0
    .max_flat_workgroup_size: 256
    .name:           _Z14fwd_megakernel6Params
    .private_segment_fixed_size: 0
    .sgpr_count:     106
    .sgpr_spill_count: 387
    .symbol:         _Z14fwd_megakernel6Params.kd
    .uniform_work_group_size: 1
    .uses_dynamic_stack: false
    .vgpr_count:     256
    .vgpr_spill_count: 0
    .wavefront_size: 64
